# P10 epilogue: 16 residual loads batched up front, counted vmcnt
# speedup vs baseline: 1.0233x; 1.0233x over previous
.LBB0_1565:
	ds_read_b128 v[148:151], v153
	ds_read_b128 v[156:159], v153 offset:1024
	ds_read_b128 v[160:163], v153 offset:2048
	ds_read_b128 v[164:167], v153 offset:3072
	ds_read_b128 v[168:171], v154
	ds_read_b128 v[172:175], v154 offset:1024
	ds_read_b128 v[176:179], v154 offset:2048
	ds_read_b128 v[180:183], v154 offset:3072
	s_add_u32 s22, s20, 0x100
	s_addc_u32 s23, s21, 0
	s_cmpk_eq_i32 s35, 0x54
	s_cselect_b32 s29, s9, s23
	s_cselect_b32 s28, s8, s22
	s_cselect_b32 s25, s11, s34
	s_cselect_b32 s24, s10, s33
	v_lshl_add_u64 v[218:219], s[20:21], 0, v[140:141]
	s_add_i32 m0, s31, 0xc000
	ds_read_b128 v[184:187], v155
	ds_read_b128 v[188:191], v155 offset:1024
	ds_read_b128 v[192:195], v155 offset:2048
	ds_read_b128 v[196:199], v155 offset:3072
	ds_read_b128 v[200:203], v155 offset:4096
	ds_read_b128 v[204:207], v155 offset:5120
	ds_read_b128 v[208:211], v155 offset:6144
	ds_read_b128 v[214:217], v155 offset:7168
	global_load_lds_dwordx4 v[218:219], off
	v_lshl_add_u64 v[218:219], s[20:21], 0, v[142:143]
	s_add_i32 m0, s31, 0xe000
	s_nop 0
	global_load_lds_dwordx4 v[218:219], off
	s_waitcnt vmcnt(8)
	s_waitcnt lgkmcnt(0)
	s_barrier
	s_setprio 1
	s_waitcnt lgkmcnt(0)
	v_mfma_f32_16x16x32_bf16 v[124:127], v[148:151], v[184:187], v[124:127]
	v_mfma_f32_16x16x32_bf16 v[120:123], v[160:163], v[184:187], v[120:123]
	v_mfma_f32_16x16x32_bf16 v[108:111], v[148:151], v[192:195], v[108:111]
	v_mfma_f32_16x16x32_bf16 v[104:107], v[160:163], v[192:195], v[104:107]
	v_mfma_f32_16x16x32_bf16 v[92:95], v[148:151], v[200:203], v[92:95]
	v_mfma_f32_16x16x32_bf16 v[88:91], v[160:163], v[200:203], v[88:91]
	v_mfma_f32_16x16x32_bf16 v[76:79], v[148:151], v[208:211], v[76:79]
	v_mfma_f32_16x16x32_bf16 v[72:75], v[160:163], v[208:211], v[72:75]
	v_mfma_f32_16x16x32_bf16 v[124:127], v[156:159], v[188:191], v[124:127]
	v_mfma_f32_16x16x32_bf16 v[120:123], v[164:167], v[188:191], v[120:123]
	v_mfma_f32_16x16x32_bf16 v[108:111], v[156:159], v[196:199], v[108:111]
	v_mfma_f32_16x16x32_bf16 v[104:107], v[164:167], v[196:199], v[104:107]
	v_mfma_f32_16x16x32_bf16 v[92:95], v[156:159], v[204:207], v[92:95]
	v_mfma_f32_16x16x32_bf16 v[88:91], v[164:167], v[204:207], v[88:91]
	v_mfma_f32_16x16x32_bf16 v[76:79], v[156:159], v[214:217], v[76:79]
	v_mfma_f32_16x16x32_bf16 v[72:75], v[164:167], v[214:217], v[72:75]
	s_setprio 0
	s_setprio 1
	v_mfma_f32_16x16x32_bf16 v[116:119], v[168:171], v[184:187], v[116:119]
	v_mfma_f32_16x16x32_bf16 v[112:115], v[176:179], v[184:187], v[112:115]
	v_mfma_f32_16x16x32_bf16 v[100:103], v[168:171], v[192:195], v[100:103]
	v_mfma_f32_16x16x32_bf16 v[96:99], v[176:179], v[192:195], v[96:99]
	v_mfma_f32_16x16x32_bf16 v[84:87], v[168:171], v[200:203], v[84:87]
	v_mfma_f32_16x16x32_bf16 v[80:83], v[176:179], v[200:203], v[80:83]
	v_mfma_f32_16x16x32_bf16 v[68:71], v[168:171], v[208:211], v[68:71]
	v_mfma_f32_16x16x32_bf16 v[64:67], v[176:179], v[208:211], v[64:67]
	v_mfma_f32_16x16x32_bf16 v[116:119], v[172:175], v[188:191], v[116:119]
	v_mfma_f32_16x16x32_bf16 v[112:115], v[180:183], v[188:191], v[112:115]
	v_mfma_f32_16x16x32_bf16 v[100:103], v[172:175], v[196:199], v[100:103]
	v_mfma_f32_16x16x32_bf16 v[96:99], v[180:183], v[196:199], v[96:99]
	v_mfma_f32_16x16x32_bf16 v[84:87], v[172:175], v[204:207], v[84:87]
	v_mfma_f32_16x16x32_bf16 v[80:83], v[180:183], v[204:207], v[80:83]
	v_mfma_f32_16x16x32_bf16 v[68:71], v[172:175], v[214:217], v[68:71]
	v_mfma_f32_16x16x32_bf16 v[64:67], v[180:183], v[214:217], v[64:67]
	s_setprio 0
	s_barrier
	s_add_i32 s20, s46, s30
	v_lshl_add_u64 v[218:219], s[24:25], 0, v[132:133]
	s_mov_b32 m0, s20
	ds_read_b128 v[184:187], v155 offset:16384
	ds_read_b128 v[188:191], v155 offset:17408
	ds_read_b128 v[192:195], v155 offset:18432
	ds_read_b128 v[196:199], v155 offset:19456
	ds_read_b128 v[200:203], v155 offset:20480
	ds_read_b128 v[204:207], v155 offset:21504
	ds_read_b128 v[208:211], v155 offset:22528
	ds_read_b128 v[214:217], v155 offset:23552
	global_load_lds_dwordx4 v[218:219], off
	s_add_i32 m0, s20, 0x2000
	s_add_u32 s20, s24, 0x160000
	v_lshl_add_u64 v[220:221], s[24:25], 0, v[136:137]
	s_addc_u32 s21, s25, 0
	s_add_i32 s50, s47, s30
	global_load_lds_dwordx4 v[220:221], off
	v_lshl_add_u64 v[222:223], s[20:21], 0, v[132:133]
	s_mov_b32 m0, s50
	v_lshl_add_u64 v[224:225], s[28:29], 0, v[134:135]
	global_load_lds_dwordx4 v[222:223], off
	v_lshl_add_u64 v[222:223], s[20:21], 0, v[136:137]
	s_add_i32 m0, s50, 0x2000
	s_nop 0
	global_load_lds_dwordx4 v[222:223], off
	v_lshl_add_u64 v[222:223], s[28:29], 0, v[130:131]
	s_mov_b32 m0, s31
	s_nop 0
	global_load_lds_dwordx4 v[222:223], off
	s_mov_b32 m0, s36
	s_nop 0
	global_load_lds_dwordx4 v[224:225], off
	s_waitcnt vmcnt(8)
	s_waitcnt lgkmcnt(0)
	s_barrier
	s_setprio 1
	s_waitcnt lgkmcnt(0)
	v_mfma_f32_16x16x32_bf16 v[60:63], v[148:151], v[184:187], v[60:63]
	v_mfma_f32_16x16x32_bf16 v[56:59], v[160:163], v[184:187], v[56:59]
	v_mfma_f32_16x16x32_bf16 v[44:47], v[148:151], v[192:195], v[44:47]
	v_mfma_f32_16x16x32_bf16 v[40:43], v[160:163], v[192:195], v[40:43]
	v_mfma_f32_16x16x32_bf16 v[28:31], v[148:151], v[200:203], v[28:31]
	v_mfma_f32_16x16x32_bf16 v[24:27], v[160:163], v[200:203], v[24:27]
	v_mfma_f32_16x16x32_bf16 v[12:15], v[148:151], v[208:211], v[12:15]
	v_mfma_f32_16x16x32_bf16 v[8:11], v[160:163], v[208:211], v[8:11]
	v_mfma_f32_16x16x32_bf16 v[60:63], v[156:159], v[188:191], v[60:63]
	v_mfma_f32_16x16x32_bf16 v[56:59], v[164:167], v[188:191], v[56:59]
	v_mfma_f32_16x16x32_bf16 v[44:47], v[156:159], v[196:199], v[44:47]
	v_mfma_f32_16x16x32_bf16 v[40:43], v[164:167], v[196:199], v[40:43]
	v_mfma_f32_16x16x32_bf16 v[28:31], v[156:159], v[204:207], v[28:31]
	v_mfma_f32_16x16x32_bf16 v[24:27], v[164:167], v[204:207], v[24:27]
	v_mfma_f32_16x16x32_bf16 v[12:15], v[156:159], v[214:217], v[12:15]
	v_mfma_f32_16x16x32_bf16 v[8:11], v[164:167], v[214:217], v[8:11]
	s_setprio 0
	s_setprio 1
	v_mfma_f32_16x16x32_bf16 v[52:55], v[168:171], v[184:187], v[52:55]
	v_mfma_f32_16x16x32_bf16 v[48:51], v[176:179], v[184:187], v[48:51]
	v_mfma_f32_16x16x32_bf16 v[36:39], v[168:171], v[192:195], v[36:39]
	v_mfma_f32_16x16x32_bf16 v[32:35], v[176:179], v[192:195], v[32:35]
	v_mfma_f32_16x16x32_bf16 v[20:23], v[168:171], v[200:203], v[20:23]
	v_mfma_f32_16x16x32_bf16 v[16:19], v[176:179], v[200:203], v[16:19]
	v_mfma_f32_16x16x32_bf16 v[4:7], v[168:171], v[208:211], v[4:7]
	v_mfma_f32_16x16x32_bf16 v[0:3], v[176:179], v[208:211], v[0:3]
	v_mfma_f32_16x16x32_bf16 v[52:55], v[172:175], v[188:191], v[52:55]
	v_mfma_f32_16x16x32_bf16 v[48:51], v[180:183], v[188:191], v[48:51]
	v_mfma_f32_16x16x32_bf16 v[36:39], v[172:175], v[196:199], v[36:39]
	v_mfma_f32_16x16x32_bf16 v[32:35], v[180:183], v[196:199], v[32:35]
	v_mfma_f32_16x16x32_bf16 v[20:23], v[172:175], v[204:207], v[20:23]
	v_mfma_f32_16x16x32_bf16 v[16:19], v[180:183], v[204:207], v[16:19]
	v_mfma_f32_16x16x32_bf16 v[4:7], v[172:175], v[214:217], v[4:7]
	v_mfma_f32_16x16x32_bf16 v[0:3], v[180:183], v[214:217], v[0:3]
	s_setprio 0
	s_barrier
	s_add_i32 s50, 0, 0x18000
	s_add_i32 s51, 0, 0x1c000
	v_add_u32_e32 v164, s50, v139
	v_add_u32_e32 v180, s51, v139
	ds_read_b128 v[148:151], v164
	ds_read_b128 v[156:159], v164 offset:1024
	ds_read_b128 v[160:163], v164 offset:2048
	ds_read_b128 v[164:167], v164 offset:3072
	ds_read_b128 v[168:171], v180
	ds_read_b128 v[172:175], v180 offset:1024
	ds_read_b128 v[176:179], v180 offset:2048
	ds_read_b128 v[180:183], v180 offset:3072
	s_add_u32 s20, s28, 0x160000
	s_addc_u32 s21, s29, 0
	s_mov_b32 m0, s37
	v_lshl_add_u64 v[226:227], s[20:21], 0, v[130:131]
	ds_read_b128 v[184:187], v155 offset:32768
	ds_read_b128 v[188:191], v155 offset:33792
	ds_read_b128 v[192:195], v155 offset:34816
	ds_read_b128 v[196:199], v155 offset:35840
	ds_read_b128 v[200:203], v155 offset:36864
	ds_read_b128 v[204:207], v155 offset:37888
	ds_read_b128 v[208:211], v155 offset:38912
	ds_read_b128 v[214:217], v155 offset:39936
	global_load_lds_dwordx4 v[226:227], off
	v_lshl_add_u64 v[226:227], s[20:21], 0, v[134:135]
	s_mov_b32 m0, s38
	s_nop 0
	global_load_lds_dwordx4 v[226:227], off
	s_waitcnt vmcnt(8)
	s_waitcnt lgkmcnt(0)
	s_barrier
	s_setprio 1
	s_waitcnt lgkmcnt(0)
	v_mfma_f32_16x16x32_bf16 v[124:127], v[148:151], v[184:187], v[124:127]
	v_mfma_f32_16x16x32_bf16 v[120:123], v[160:163], v[184:187], v[120:123]
	v_mfma_f32_16x16x32_bf16 v[108:111], v[148:151], v[192:195], v[108:111]
	v_mfma_f32_16x16x32_bf16 v[104:107], v[160:163], v[192:195], v[104:107]
	v_mfma_f32_16x16x32_bf16 v[92:95], v[148:151], v[200:203], v[92:95]
	v_mfma_f32_16x16x32_bf16 v[88:91], v[160:163], v[200:203], v[88:91]
	v_mfma_f32_16x16x32_bf16 v[76:79], v[148:151], v[208:211], v[76:79]
	v_mfma_f32_16x16x32_bf16 v[72:75], v[160:163], v[208:211], v[72:75]
	v_mfma_f32_16x16x32_bf16 v[124:127], v[156:159], v[188:191], v[124:127]
	v_mfma_f32_16x16x32_bf16 v[120:123], v[164:167], v[188:191], v[120:123]
	v_mfma_f32_16x16x32_bf16 v[108:111], v[156:159], v[196:199], v[108:111]
	v_mfma_f32_16x16x32_bf16 v[104:107], v[164:167], v[196:199], v[104:107]
	v_mfma_f32_16x16x32_bf16 v[92:95], v[156:159], v[204:207], v[92:95]
	v_mfma_f32_16x16x32_bf16 v[88:91], v[164:167], v[204:207], v[88:91]
	v_mfma_f32_16x16x32_bf16 v[76:79], v[156:159], v[214:217], v[76:79]
	v_mfma_f32_16x16x32_bf16 v[72:75], v[164:167], v[214:217], v[72:75]
	s_setprio 0
	s_setprio 1
	v_mfma_f32_16x16x32_bf16 v[116:119], v[168:171], v[184:187], v[116:119]
	v_mfma_f32_16x16x32_bf16 v[112:115], v[176:179], v[184:187], v[112:115]
	v_mfma_f32_16x16x32_bf16 v[100:103], v[168:171], v[192:195], v[100:103]
	v_mfma_f32_16x16x32_bf16 v[96:99], v[176:179], v[192:195], v[96:99]
	v_mfma_f32_16x16x32_bf16 v[84:87], v[168:171], v[200:203], v[84:87]
	v_mfma_f32_16x16x32_bf16 v[80:83], v[176:179], v[200:203], v[80:83]
	v_mfma_f32_16x16x32_bf16 v[68:71], v[168:171], v[208:211], v[68:71]
	v_mfma_f32_16x16x32_bf16 v[64:67], v[176:179], v[208:211], v[64:67]
	v_mfma_f32_16x16x32_bf16 v[116:119], v[172:175], v[188:191], v[116:119]
	v_mfma_f32_16x16x32_bf16 v[112:115], v[180:183], v[188:191], v[112:115]
	v_mfma_f32_16x16x32_bf16 v[100:103], v[172:175], v[196:199], v[100:103]
	v_mfma_f32_16x16x32_bf16 v[96:99], v[180:183], v[196:199], v[96:99]
	v_mfma_f32_16x16x32_bf16 v[84:87], v[172:175], v[204:207], v[84:87]
	v_mfma_f32_16x16x32_bf16 v[80:83], v[180:183], v[204:207], v[80:83]
	v_mfma_f32_16x16x32_bf16 v[68:71], v[172:175], v[214:217], v[68:71]
	v_mfma_f32_16x16x32_bf16 v[64:67], v[180:183], v[214:217], v[64:67]
	s_setprio 0
	s_barrier
	s_add_i32 s20, s50, s30
	v_lshl_add_u64 v[218:219], v[218:219], 0, s[16:17]
	s_mov_b32 m0, s20
	ds_read_b128 v[184:187], v155 offset:49152
	ds_read_b128 v[188:191], v155 offset:50176
	ds_read_b128 v[192:195], v155 offset:51200
	ds_read_b128 v[196:199], v155 offset:52224
	ds_read_b128 v[200:203], v155 offset:53248
	ds_read_b128 v[204:207], v155 offset:54272
	ds_read_b128 v[208:211], v155 offset:55296
	ds_read_b128 v[214:217], v155 offset:56320
	global_load_lds_dwordx4 v[218:219], off
	s_add_i32 m0, s20, 0x2000
	s_add_u32 s20, s24, 0x160080
	v_lshl_add_u64 v[218:219], v[220:221], 0, s[16:17]
	s_addc_u32 s21, s25, 0
	s_add_i32 s24, s51, s30
	global_load_lds_dwordx4 v[218:219], off
	v_lshl_add_u64 v[218:219], s[20:21], 0, v[132:133]
	s_mov_b32 m0, s24
	s_nop 0
	global_load_lds_dwordx4 v[218:219], off
	v_lshl_add_u64 v[218:219], s[20:21], 0, v[136:137]
	s_add_i32 m0, s24, 0x2000
	s_nop 0
	global_load_lds_dwordx4 v[218:219], off
	v_lshl_add_u64 v[218:219], v[222:223], 0, s[16:17]
	s_mov_b32 m0, s42
	s_nop 0
	global_load_lds_dwordx4 v[218:219], off
	v_lshl_add_u64 v[218:219], v[224:225], 0, s[16:17]
	s_mov_b32 m0, s43
	s_nop 0
	global_load_lds_dwordx4 v[218:219], off
	s_waitcnt vmcnt(8)
	s_waitcnt lgkmcnt(0)
	s_barrier
	s_setprio 1
	s_waitcnt lgkmcnt(0)
	v_mfma_f32_16x16x32_bf16 v[60:63], v[148:151], v[184:187], v[60:63]
	v_mfma_f32_16x16x32_bf16 v[56:59], v[160:163], v[184:187], v[56:59]
	v_mfma_f32_16x16x32_bf16 v[44:47], v[148:151], v[192:195], v[44:47]
	v_mfma_f32_16x16x32_bf16 v[40:43], v[160:163], v[192:195], v[40:43]
	v_mfma_f32_16x16x32_bf16 v[28:31], v[148:151], v[200:203], v[28:31]
	v_mfma_f32_16x16x32_bf16 v[24:27], v[160:163], v[200:203], v[24:27]
	v_mfma_f32_16x16x32_bf16 v[12:15], v[148:151], v[208:211], v[12:15]
	v_mfma_f32_16x16x32_bf16 v[8:11], v[160:163], v[208:211], v[8:11]
	v_mfma_f32_16x16x32_bf16 v[60:63], v[156:159], v[188:191], v[60:63]
	v_mfma_f32_16x16x32_bf16 v[56:59], v[164:167], v[188:191], v[56:59]
	v_mfma_f32_16x16x32_bf16 v[44:47], v[156:159], v[196:199], v[44:47]
	v_mfma_f32_16x16x32_bf16 v[40:43], v[164:167], v[196:199], v[40:43]
	v_mfma_f32_16x16x32_bf16 v[28:31], v[156:159], v[204:207], v[28:31]
	v_mfma_f32_16x16x32_bf16 v[24:27], v[164:167], v[204:207], v[24:27]
	v_mfma_f32_16x16x32_bf16 v[12:15], v[156:159], v[214:217], v[12:15]
	v_mfma_f32_16x16x32_bf16 v[8:11], v[164:167], v[214:217], v[8:11]
	s_setprio 0
	s_setprio 1
	v_mfma_f32_16x16x32_bf16 v[52:55], v[168:171], v[184:187], v[52:55]
	v_mfma_f32_16x16x32_bf16 v[48:51], v[176:179], v[184:187], v[48:51]
	v_mfma_f32_16x16x32_bf16 v[36:39], v[168:171], v[192:195], v[36:39]
	v_mfma_f32_16x16x32_bf16 v[32:35], v[176:179], v[192:195], v[32:35]
	v_mfma_f32_16x16x32_bf16 v[20:23], v[168:171], v[200:203], v[20:23]
	v_mfma_f32_16x16x32_bf16 v[16:19], v[176:179], v[200:203], v[16:19]
	v_mfma_f32_16x16x32_bf16 v[4:7], v[168:171], v[208:211], v[4:7]
	v_mfma_f32_16x16x32_bf16 v[0:3], v[176:179], v[208:211], v[0:3]
	v_mfma_f32_16x16x32_bf16 v[52:55], v[172:175], v[188:191], v[52:55]
	v_mfma_f32_16x16x32_bf16 v[48:51], v[180:183], v[188:191], v[48:51]
	v_mfma_f32_16x16x32_bf16 v[36:39], v[172:175], v[196:199], v[36:39]
	v_mfma_f32_16x16x32_bf16 v[32:35], v[180:183], v[196:199], v[32:35]
	v_mfma_f32_16x16x32_bf16 v[20:23], v[172:175], v[204:207], v[20:23]
	v_mfma_f32_16x16x32_bf16 v[16:19], v[180:183], v[204:207], v[16:19]
	v_mfma_f32_16x16x32_bf16 v[4:7], v[172:175], v[214:217], v[4:7]
	v_mfma_f32_16x16x32_bf16 v[0:3], v[180:183], v[214:217], v[0:3]
	s_setprio 0
	s_barrier
	s_add_i32 s35, s35, 2
	s_add_u32 s33, s33, 0x100
	s_addc_u32 s34, s34, 0
	s_cmpk_gt_u32 s35, 0x55
	s_mov_b64 s[20:21], s[22:23]
	s_cbranch_scc0 .LBB0_1565
	v_lshl_add_u32 v150, s14, 8, v129
	s_lshl_b32 s14, s15, 8
	v_or_b32_e32 v148, s14, v138
	s_and_b64 vcc, exec, s[6:7]
	s_mov_b32 s15, s48
	s_mov_b32 s14, s49
	s_mov_b64 s[22:23], s[10:11]
	s_mov_b64 s[20:21], s[8:9]
	v_lshlrev_b32_e32 v149, 1, v148
	v_lshlrev_b32_e32 v148, 2, v148
	v_lshl_add_u32 v151, v150, 12, v149
	global_load_dwordx4 v[156:159], v151, s[40:41]
	global_load_dwordx4 v[160:163], v151, s[40:41] offset:256
	v_add_u32_e32 v222, 16, v150
	v_lshl_add_u32 v223, v222, 12, v149
	global_load_dwordx4 v[164:167], v223, s[40:41]
	global_load_dwordx4 v[168:171], v223, s[40:41] offset:256
	v_add_u32_e32 v222, 32, v150
	v_lshl_add_u32 v151, v222, 12, v149
	global_load_dwordx4 v[172:175], v151, s[40:41]
	global_load_dwordx4 v[176:179], v151, s[40:41] offset:256
	v_add_u32_e32 v222, 48, v150
	v_lshl_add_u32 v223, v222, 12, v149
	global_load_dwordx4 v[180:183], v223, s[40:41]
	global_load_dwordx4 v[184:187], v223, s[40:41] offset:256
	v_add_u32_e32 v222, 0x80, v150
	v_lshl_add_u32 v151, v222, 12, v149
	global_load_dwordx4 v[188:191], v151, s[40:41]
	global_load_dwordx4 v[192:195], v151, s[40:41] offset:256
	v_add_u32_e32 v222, 0x90, v150
	v_lshl_add_u32 v223, v222, 12, v149
	global_load_dwordx4 v[196:199], v223, s[40:41]
	global_load_dwordx4 v[200:203], v223, s[40:41] offset:256
	v_add_u32_e32 v222, 0xa0, v150
	v_lshl_add_u32 v151, v222, 12, v149
	global_load_dwordx4 v[204:207], v151, s[40:41]
	global_load_dwordx4 v[208:211], v151, s[40:41] offset:256
	v_add_u32_e32 v222, 0xb0, v150
	v_lshl_add_u32 v223, v222, 12, v149
	global_load_dwordx4 v[214:217], v223, s[40:41]
	global_load_dwordx4 v[218:221], v223, s[40:41] offset:256
	v_lshl_add_u32 v151, v150, 13, v148
	s_waitcnt vmcnt(15)
	v_lshlrev_b32_e32 v224, 16, v156
	v_and_b32_e32 v225, 0xffff0000, v156
	v_lshlrev_b32_e32 v156, 16, v157
	v_and_b32_e32 v157, 0xffff0000, v157
	v_lshlrev_b32_e32 v226, 16, v158
	v_and_b32_e32 v227, 0xffff0000, v158
	v_lshlrev_b32_e32 v158, 16, v159
	v_and_b32_e32 v159, 0xffff0000, v159
	v_pk_fma_f32 v[126:127], v[156:157], s[18:19], v[126:127] op_sel_hi:[1,0,1]
	v_pk_fma_f32 v[124:125], v[224:225], s[18:19], v[124:125] op_sel_hi:[1,0,1]
	v_pk_fma_f32 v[122:123], v[158:159], s[18:19], v[122:123] op_sel_hi:[1,0,1]
	v_pk_fma_f32 v[120:121], v[226:227], s[18:19], v[120:121] op_sel_hi:[1,0,1]
	global_store_dwordx4 v151, v[124:127], s[12:13]
	global_store_dwordx4 v151, v[120:123], s[12:13] offset:16
	s_waitcnt vmcnt(16)
	v_lshlrev_b32_e32 v224, 16, v160
	v_and_b32_e32 v225, 0xffff0000, v160
	v_lshlrev_b32_e32 v160, 16, v161
	v_and_b32_e32 v161, 0xffff0000, v161
	v_lshlrev_b32_e32 v226, 16, v162
	v_and_b32_e32 v227, 0xffff0000, v162
	v_lshlrev_b32_e32 v162, 16, v163
	v_and_b32_e32 v163, 0xffff0000, v163
	v_pk_fma_f32 v[118:119], v[160:161], s[18:19], v[118:119] op_sel_hi:[1,0,1]
	v_pk_fma_f32 v[116:117], v[224:225], s[18:19], v[116:117] op_sel_hi:[1,0,1]
	v_pk_fma_f32 v[114:115], v[162:163], s[18:19], v[114:115] op_sel_hi:[1,0,1]
	v_pk_fma_f32 v[112:113], v[226:227], s[18:19], v[112:113] op_sel_hi:[1,0,1]
	global_store_dwordx4 v151, v[116:119], s[12:13] offset:512
	global_store_dwordx4 v151, v[112:115], s[12:13] offset:528
	v_add_u32_e32 v222, 16, v150
	v_lshl_add_u32 v223, v222, 13, v148
	s_waitcnt vmcnt(17)
	v_lshlrev_b32_e32 v224, 16, v164
	v_and_b32_e32 v225, 0xffff0000, v164
	v_lshlrev_b32_e32 v164, 16, v165
	v_and_b32_e32 v165, 0xffff0000, v165
	v_lshlrev_b32_e32 v226, 16, v166
	v_and_b32_e32 v227, 0xffff0000, v166
	v_lshlrev_b32_e32 v166, 16, v167
	v_and_b32_e32 v167, 0xffff0000, v167
	v_pk_fma_f32 v[110:111], v[164:165], s[18:19], v[110:111] op_sel_hi:[1,0,1]
	v_pk_fma_f32 v[108:109], v[224:225], s[18:19], v[108:109] op_sel_hi:[1,0,1]
	v_pk_fma_f32 v[106:107], v[166:167], s[18:19], v[106:107] op_sel_hi:[1,0,1]
	v_pk_fma_f32 v[104:105], v[226:227], s[18:19], v[104:105] op_sel_hi:[1,0,1]
	global_store_dwordx4 v223, v[108:111], s[12:13]
	global_store_dwordx4 v223, v[104:107], s[12:13] offset:16
	s_waitcnt vmcnt(18)
	v_lshlrev_b32_e32 v224, 16, v168
	v_and_b32_e32 v225, 0xffff0000, v168
	v_lshlrev_b32_e32 v168, 16, v169
	v_and_b32_e32 v169, 0xffff0000, v169
	v_lshlrev_b32_e32 v226, 16, v170
	v_and_b32_e32 v227, 0xffff0000, v170
	v_lshlrev_b32_e32 v170, 16, v171
	v_and_b32_e32 v171, 0xffff0000, v171
	v_pk_fma_f32 v[102:103], v[168:169], s[18:19], v[102:103] op_sel_hi:[1,0,1]
	v_pk_fma_f32 v[100:101], v[224:225], s[18:19], v[100:101] op_sel_hi:[1,0,1]
	v_pk_fma_f32 v[98:99], v[170:171], s[18:19], v[98:99] op_sel_hi:[1,0,1]
	v_pk_fma_f32 v[96:97], v[226:227], s[18:19], v[96:97] op_sel_hi:[1,0,1]
	global_store_dwordx4 v223, v[100:103], s[12:13] offset:512
	global_store_dwordx4 v223, v[96:99], s[12:13] offset:528
	v_add_u32_e32 v222, 32, v150
	v_lshl_add_u32 v151, v222, 13, v148
	s_waitcnt vmcnt(19)
	v_lshlrev_b32_e32 v224, 16, v172
	v_and_b32_e32 v225, 0xffff0000, v172
	v_lshlrev_b32_e32 v172, 16, v173
	v_and_b32_e32 v173, 0xffff0000, v173
	v_lshlrev_b32_e32 v226, 16, v174
	v_and_b32_e32 v227, 0xffff0000, v174
	v_lshlrev_b32_e32 v174, 16, v175
	v_and_b32_e32 v175, 0xffff0000, v175
	v_pk_fma_f32 v[94:95], v[172:173], s[18:19], v[94:95] op_sel_hi:[1,0,1]
	v_pk_fma_f32 v[92:93], v[224:225], s[18:19], v[92:93] op_sel_hi:[1,0,1]
	v_pk_fma_f32 v[90:91], v[174:175], s[18:19], v[90:91] op_sel_hi:[1,0,1]
	v_pk_fma_f32 v[88:89], v[226:227], s[18:19], v[88:89] op_sel_hi:[1,0,1]
	global_store_dwordx4 v151, v[92:95], s[12:13]
	global_store_dwordx4 v151, v[88:91], s[12:13] offset:16
	s_waitcnt vmcnt(20)
	v_lshlrev_b32_e32 v224, 16, v176
	v_and_b32_e32 v225, 0xffff0000, v176
	v_lshlrev_b32_e32 v176, 16, v177
	v_and_b32_e32 v177, 0xffff0000, v177
	v_lshlrev_b32_e32 v226, 16, v178
	v_and_b32_e32 v227, 0xffff0000, v178
	v_lshlrev_b32_e32 v178, 16, v179
	v_and_b32_e32 v179, 0xffff0000, v179
	v_pk_fma_f32 v[86:87], v[176:177], s[18:19], v[86:87] op_sel_hi:[1,0,1]
	v_pk_fma_f32 v[84:85], v[224:225], s[18:19], v[84:85] op_sel_hi:[1,0,1]
	v_pk_fma_f32 v[82:83], v[178:179], s[18:19], v[82:83] op_sel_hi:[1,0,1]
	v_pk_fma_f32 v[80:81], v[226:227], s[18:19], v[80:81] op_sel_hi:[1,0,1]
	global_store_dwordx4 v151, v[84:87], s[12:13] offset:512
	global_store_dwordx4 v151, v[80:83], s[12:13] offset:528
	v_add_u32_e32 v222, 48, v150
	v_lshl_add_u32 v223, v222, 13, v148
	s_waitcnt vmcnt(21)
	v_lshlrev_b32_e32 v224, 16, v180
	v_and_b32_e32 v225, 0xffff0000, v180
	v_lshlrev_b32_e32 v180, 16, v181
	v_and_b32_e32 v181, 0xffff0000, v181
	v_lshlrev_b32_e32 v226, 16, v182
	v_and_b32_e32 v227, 0xffff0000, v182
	v_lshlrev_b32_e32 v182, 16, v183
	v_and_b32_e32 v183, 0xffff0000, v183
	v_pk_fma_f32 v[78:79], v[180:181], s[18:19], v[78:79] op_sel_hi:[1,0,1]
	v_pk_fma_f32 v[76:77], v[224:225], s[18:19], v[76:77] op_sel_hi:[1,0,1]
	v_pk_fma_f32 v[74:75], v[182:183], s[18:19], v[74:75] op_sel_hi:[1,0,1]
	v_pk_fma_f32 v[72:73], v[226:227], s[18:19], v[72:73] op_sel_hi:[1,0,1]
	global_store_dwordx4 v223, v[76:79], s[12:13]
	global_store_dwordx4 v223, v[72:75], s[12:13] offset:16
	s_waitcnt vmcnt(22)
	v_lshlrev_b32_e32 v224, 16, v184
	v_and_b32_e32 v225, 0xffff0000, v184
	v_lshlrev_b32_e32 v184, 16, v185
	v_and_b32_e32 v185, 0xffff0000, v185
	v_lshlrev_b32_e32 v226, 16, v186
	v_and_b32_e32 v227, 0xffff0000, v186
	v_lshlrev_b32_e32 v186, 16, v187
	v_and_b32_e32 v187, 0xffff0000, v187
	v_pk_fma_f32 v[70:71], v[184:185], s[18:19], v[70:71] op_sel_hi:[1,0,1]
	v_pk_fma_f32 v[68:69], v[224:225], s[18:19], v[68:69] op_sel_hi:[1,0,1]
	v_pk_fma_f32 v[66:67], v[186:187], s[18:19], v[66:67] op_sel_hi:[1,0,1]
	v_pk_fma_f32 v[64:65], v[226:227], s[18:19], v[64:65] op_sel_hi:[1,0,1]
	global_store_dwordx4 v223, v[68:71], s[12:13] offset:512
	global_store_dwordx4 v223, v[64:67], s[12:13] offset:528
	v_add_u32_e32 v222, 0x80, v150
	v_lshl_add_u32 v151, v222, 13, v148
	s_waitcnt vmcnt(23)
	v_lshlrev_b32_e32 v224, 16, v188
	v_and_b32_e32 v225, 0xffff0000, v188
	v_lshlrev_b32_e32 v188, 16, v189
	v_and_b32_e32 v189, 0xffff0000, v189
	v_lshlrev_b32_e32 v226, 16, v190
	v_and_b32_e32 v227, 0xffff0000, v190
	v_lshlrev_b32_e32 v190, 16, v191
	v_and_b32_e32 v191, 0xffff0000, v191
	v_pk_fma_f32 v[62:63], v[188:189], s[18:19], v[62:63] op_sel_hi:[1,0,1]
	v_pk_fma_f32 v[60:61], v[224:225], s[18:19], v[60:61] op_sel_hi:[1,0,1]
	v_pk_fma_f32 v[58:59], v[190:191], s[18:19], v[58:59] op_sel_hi:[1,0,1]
	v_pk_fma_f32 v[56:57], v[226:227], s[18:19], v[56:57] op_sel_hi:[1,0,1]
	global_store_dwordx4 v151, v[60:63], s[12:13]
	global_store_dwordx4 v151, v[56:59], s[12:13] offset:16
	s_waitcnt vmcnt(24)
	v_lshlrev_b32_e32 v224, 16, v192
	v_and_b32_e32 v225, 0xffff0000, v192
	v_lshlrev_b32_e32 v192, 16, v193
	v_and_b32_e32 v193, 0xffff0000, v193
	v_lshlrev_b32_e32 v226, 16, v194
	v_and_b32_e32 v227, 0xffff0000, v194
	v_lshlrev_b32_e32 v194, 16, v195
	v_and_b32_e32 v195, 0xffff0000, v195
	v_pk_fma_f32 v[54:55], v[192:193], s[18:19], v[54:55] op_sel_hi:[1,0,1]
	v_pk_fma_f32 v[52:53], v[224:225], s[18:19], v[52:53] op_sel_hi:[1,0,1]
	v_pk_fma_f32 v[50:51], v[194:195], s[18:19], v[50:51] op_sel_hi:[1,0,1]
	v_pk_fma_f32 v[48:49], v[226:227], s[18:19], v[48:49] op_sel_hi:[1,0,1]
	global_store_dwordx4 v151, v[52:55], s[12:13] offset:512
	global_store_dwordx4 v151, v[48:51], s[12:13] offset:528
	v_add_u32_e32 v222, 0x90, v150
	v_lshl_add_u32 v223, v222, 13, v148
	s_waitcnt vmcnt(25)
	v_lshlrev_b32_e32 v224, 16, v196
	v_and_b32_e32 v225, 0xffff0000, v196
	v_lshlrev_b32_e32 v196, 16, v197
	v_and_b32_e32 v197, 0xffff0000, v197
	v_lshlrev_b32_e32 v226, 16, v198
	v_and_b32_e32 v227, 0xffff0000, v198
	v_lshlrev_b32_e32 v198, 16, v199
	v_and_b32_e32 v199, 0xffff0000, v199
	v_pk_fma_f32 v[46:47], v[196:197], s[18:19], v[46:47] op_sel_hi:[1,0,1]
	v_pk_fma_f32 v[44:45], v[224:225], s[18:19], v[44:45] op_sel_hi:[1,0,1]
	v_pk_fma_f32 v[42:43], v[198:199], s[18:19], v[42:43] op_sel_hi:[1,0,1]
	v_pk_fma_f32 v[40:41], v[226:227], s[18:19], v[40:41] op_sel_hi:[1,0,1]
	global_store_dwordx4 v223, v[44:47], s[12:13]
	global_store_dwordx4 v223, v[40:43], s[12:13] offset:16
	s_waitcnt vmcnt(26)
	v_lshlrev_b32_e32 v224, 16, v200
	v_and_b32_e32 v225, 0xffff0000, v200
	v_lshlrev_b32_e32 v200, 16, v201
	v_and_b32_e32 v201, 0xffff0000, v201
	v_lshlrev_b32_e32 v226, 16, v202
	v_and_b32_e32 v227, 0xffff0000, v202
	v_lshlrev_b32_e32 v202, 16, v203
	v_and_b32_e32 v203, 0xffff0000, v203
	v_pk_fma_f32 v[38:39], v[200:201], s[18:19], v[38:39] op_sel_hi:[1,0,1]
	v_pk_fma_f32 v[36:37], v[224:225], s[18:19], v[36:37] op_sel_hi:[1,0,1]
	v_pk_fma_f32 v[34:35], v[202:203], s[18:19], v[34:35] op_sel_hi:[1,0,1]
	v_pk_fma_f32 v[32:33], v[226:227], s[18:19], v[32:33] op_sel_hi:[1,0,1]
	global_store_dwordx4 v223, v[36:39], s[12:13] offset:512
	global_store_dwordx4 v223, v[32:35], s[12:13] offset:528
	v_add_u32_e32 v222, 0xa0, v150
	v_lshl_add_u32 v151, v222, 13, v148
	s_waitcnt vmcnt(27)
	v_lshlrev_b32_e32 v224, 16, v204
	v_and_b32_e32 v225, 0xffff0000, v204
	v_lshlrev_b32_e32 v204, 16, v205
	v_and_b32_e32 v205, 0xffff0000, v205
	v_lshlrev_b32_e32 v226, 16, v206
	v_and_b32_e32 v227, 0xffff0000, v206
	v_lshlrev_b32_e32 v206, 16, v207
	v_and_b32_e32 v207, 0xffff0000, v207
	v_pk_fma_f32 v[30:31], v[204:205], s[18:19], v[30:31] op_sel_hi:[1,0,1]
	v_pk_fma_f32 v[28:29], v[224:225], s[18:19], v[28:29] op_sel_hi:[1,0,1]
	v_pk_fma_f32 v[26:27], v[206:207], s[18:19], v[26:27] op_sel_hi:[1,0,1]
	v_pk_fma_f32 v[24:25], v[226:227], s[18:19], v[24:25] op_sel_hi:[1,0,1]
	global_store_dwordx4 v151, v[28:31], s[12:13]
	global_store_dwordx4 v151, v[24:27], s[12:13] offset:16
	s_waitcnt vmcnt(28)
	v_lshlrev_b32_e32 v224, 16, v208
	v_and_b32_e32 v225, 0xffff0000, v208
	v_lshlrev_b32_e32 v208, 16, v209
	v_and_b32_e32 v209, 0xffff0000, v209
	v_lshlrev_b32_e32 v226, 16, v210
	v_and_b32_e32 v227, 0xffff0000, v210
	v_lshlrev_b32_e32 v210, 16, v211
	v_and_b32_e32 v211, 0xffff0000, v211
	v_pk_fma_f32 v[22:23], v[208:209], s[18:19], v[22:23] op_sel_hi:[1,0,1]
	v_pk_fma_f32 v[20:21], v[224:225], s[18:19], v[20:21] op_sel_hi:[1,0,1]
	v_pk_fma_f32 v[18:19], v[210:211], s[18:19], v[18:19] op_sel_hi:[1,0,1]
	v_pk_fma_f32 v[16:17], v[226:227], s[18:19], v[16:17] op_sel_hi:[1,0,1]
	global_store_dwordx4 v151, v[20:23], s[12:13] offset:512
	global_store_dwordx4 v151, v[16:19], s[12:13] offset:528
	v_add_u32_e32 v222, 0xb0, v150
	v_lshl_add_u32 v223, v222, 13, v148
	s_waitcnt vmcnt(29)
	v_lshlrev_b32_e32 v224, 16, v214
	v_and_b32_e32 v225, 0xffff0000, v214
	v_lshlrev_b32_e32 v214, 16, v215
	v_and_b32_e32 v215, 0xffff0000, v215
	v_lshlrev_b32_e32 v226, 16, v216
	v_and_b32_e32 v227, 0xffff0000, v216
	v_lshlrev_b32_e32 v216, 16, v217
	v_and_b32_e32 v217, 0xffff0000, v217
	v_pk_fma_f32 v[14:15], v[214:215], s[18:19], v[14:15] op_sel_hi:[1,0,1]
	v_pk_fma_f32 v[12:13], v[224:225], s[18:19], v[12:13] op_sel_hi:[1,0,1]
	v_pk_fma_f32 v[10:11], v[216:217], s[18:19], v[10:11] op_sel_hi:[1,0,1]
	v_pk_fma_f32 v[8:9], v[226:227], s[18:19], v[8:9] op_sel_hi:[1,0,1]
	global_store_dwordx4 v223, v[12:15], s[12:13]
	global_store_dwordx4 v223, v[8:11], s[12:13] offset:16
	s_waitcnt vmcnt(30)
	v_lshlrev_b32_e32 v224, 16, v218
	v_and_b32_e32 v225, 0xffff0000, v218
	v_lshlrev_b32_e32 v218, 16, v219
	v_and_b32_e32 v219, 0xffff0000, v219
	v_lshlrev_b32_e32 v226, 16, v220
	v_and_b32_e32 v227, 0xffff0000, v220
	v_lshlrev_b32_e32 v220, 16, v221
	v_and_b32_e32 v221, 0xffff0000, v221
	v_pk_fma_f32 v[6:7], v[218:219], s[18:19], v[6:7] op_sel_hi:[1,0,1]
	v_pk_fma_f32 v[4:5], v[224:225], s[18:19], v[4:5] op_sel_hi:[1,0,1]
	v_pk_fma_f32 v[2:3], v[220:221], s[18:19], v[2:3] op_sel_hi:[1,0,1]
	v_pk_fma_f32 v[0:1], v[226:227], s[18:19], v[0:1] op_sel_hi:[1,0,1]
	global_store_dwordx4 v223, v[4:7], s[12:13] offset:512
	global_store_dwordx4 v223, v[0:3], s[12:13] offset:528
	s_cbranch_vccz .LBB0_1554
	s_waitcnt vmcnt(0)
	s_cmpk_gt_u32 s0, 0xff
	s_cbranch_scc1 .LBB0_1569
	s_barrier
